# attention: V tile 8-byte columns XOR-swizzled in LDS (bank-conflict-free ds_read2_b64); chunk_scan: mid-step barrier and next-operand LDS reads moved behind the state-update MFMAs in two of four unrol
# baseline (speedup 1.0000x reference)
.LBB0_923:
	v_cvt_pk_bf16_f32 v122, v118, v119
	v_cvt_pk_bf16_f32 v123, v120, v121
	v_cvt_pk_bf16_f32 v124, v114, v115
	v_cvt_pk_bf16_f32 v125, v116, v117
	v_cvt_pk_bf16_f32 v130, v110, v111
	v_cvt_pk_bf16_f32 v131, v112, v113
	s_nop 0
	v_and_b32_e32 v102, 0xffff0000, v122
	v_lshlrev_b32_e32 v2, 16, v122
	v_sub_f32_e32 v102, v119, v102
	v_sub_f32_e32 v2, v118, v2
	v_cvt_pk_bf16_f32 v126, v2, v102
	v_and_b32_e32 v102, 0xffff0000, v123
	v_lshlrev_b32_e32 v2, 16, v123
	v_sub_f32_e32 v102, v121, v102
	v_sub_f32_e32 v2, v120, v2
	v_cvt_pk_bf16_f32 v127, v2, v102
	v_and_b32_e32 v102, 0xffff0000, v124
	v_lshlrev_b32_e32 v2, 16, v124
	v_sub_f32_e32 v102, v115, v102
	v_sub_f32_e32 v2, v114, v2
	v_cvt_pk_bf16_f32 v128, v2, v102
	v_and_b32_e32 v102, 0xffff0000, v125
	v_lshlrev_b32_e32 v2, 16, v125
	v_sub_f32_e32 v102, v117, v102
	v_sub_f32_e32 v2, v116, v2
	v_cvt_pk_bf16_f32 v129, v2, v102
	v_and_b32_e32 v102, 0xffff0000, v130
	v_lshlrev_b32_e32 v2, 16, v130
	v_sub_f32_e32 v102, v111, v102
	v_sub_f32_e32 v2, v110, v2
	v_cvt_pk_bf16_f32 v146, v2, v102
	v_and_b32_e32 v102, 0xffff0000, v131
	v_lshlrev_b32_e32 v2, 16, v131
	v_sub_f32_e32 v102, v113, v102
	v_sub_f32_e32 v2, v112, v2
	v_cvt_pk_bf16_f32 v147, v2, v102
	s_waitcnt lgkmcnt(14)
	v_mfma_f32_16x16x32_bf16 v[102:105], v[92:95], v[122:125], 0
	v_cvt_pk_bf16_f32 v132, v106, v107
	v_cvt_pk_bf16_f32 v133, v108, v109
	s_waitcnt lgkmcnt(3)
	v_mov_b32_e32 v160, v100
	v_mfma_f32_16x16x32_bf16 v[92:95], v[92:95], v[126:129], v[102:105]
	v_lshlrev_b32_e32 v2, 16, v132
	v_sub_f32_e32 v2, v106, v2
	v_and_b32_e32 v134, 0xffff0000, v132
	v_mfma_f32_16x16x32_bf16 v[92:95], v[88:91], v[130:133], v[92:95]
	v_sub_f32_e32 v134, v107, v134
	v_cvt_pk_bf16_f32 v148, v2, v134
	v_lshlrev_b32_e32 v2, 16, v133
	v_sub_f32_e32 v2, v108, v2
	v_and_b32_e32 v102, 0xffff0000, v133
	v_sub_f32_e32 v102, v109, v102
	v_cvt_pk_bf16_f32 v149, v2, v102
	v_mov_b32_e32 v2, v3
	v_mfma_f32_16x16x32_bf16 v[88:91], v[88:91], v[146:149], v[92:95]
	v_mov_b32_e32 v102, v3
	v_mov_b32_e32 v103, v3
	v_mov_b32_e32 v161, v101
	v_mfma_f32_16x16x32_bf16 v[92:95], v[76:79], v[122:125], 0
	v_mul_f32_e64 v98, v120, v98
	v_mul_f32_e64 v99, v121, v99
	v_pk_mul_f32 v[96:97], v[118:119], v[96:97]
	s_waitcnt lgkmcnt(0)
	v_mfma_f32_16x16x32_bf16 v[154:157], v[0:3], v[100:103], v[88:91]
	s_nop 0
	s_nop 1
	s_nop 0
	s_nop 0
	v_mfma_f32_16x16x32_bf16 v[102:105], v[76:79], v[126:129], v[92:95]
	s_nop 0
	s_nop 1
	s_nop 0
	s_nop 0
	s_nop 0
	v_lshl_add_u64 v[186:187], s[24:25], 0, v[184:185]
	s_mov_b32 s12, 0x1bf07000
	v_mfma_f32_16x16x32_bf16 v[102:105], v[72:75], v[130:133], v[102:105]
	s_nop 0
	s_nop 0
	s_nop 0
	s_nop 0
	v_mfma_f32_16x16x32_bf16 v[72:75], v[72:75], v[146:149], v[102:105]
	s_nop 2
	s_nop 0
	s_nop 0
	s_nop 2
	v_xor_b32_e32 v0, 0x80000000, v72
	v_xor_b32_e32 v1, 0x80000000, v73
	v_cvt_pk_bf16_f32 v158, v0, v1
	v_xor_b32_e32 v0, 0x80000000, v74
	v_xor_b32_e32 v1, 0x80000000, v75
	v_cvt_pk_bf16_f32 v159, v0, v1
	v_lshlrev_b32_e32 v0, 16, v158
	v_and_b32_e32 v1, 0xffff0000, v158
	v_sub_f32_e64 v0, -v72, v0
	v_sub_f32_e64 v1, -v73, v1
	v_mfma_f32_16x16x32_bf16 v[96:99], v[60:63], v[158:161], v[96:99]
	v_cvt_pk_bf16_f32 v0, v0, v1
	v_lshlrev_b32_e32 v1, 16, v159
	v_and_b32_e32 v2, 0xffff0000, v159
	v_sub_f32_e64 v1, -v74, v1
	v_sub_f32_e64 v2, -v75, v2
	v_cvt_pk_bf16_f32 v1, v1, v2
	v_mov_b32_e32 v2, v3
	s_nop 1
	v_mfma_f32_16x16x32_bf16 v[96:99], v[60:63], v[0:3], v[96:99]
	v_mul_f32_e64 v62, v116, v86
	v_mul_f32_e64 v63, v117, v87
	v_pk_mul_f32 v[60:61], v[114:115], v[84:85]
	s_nop 0
	s_nop 0
	v_mfma_f32_16x16x32_bf16 v[60:63], v[56:59], v[158:161], v[60:63]
	v_mfma_f32_16x16x32_bf16 v[146:149], v[56:59], v[0:3], v[60:63]
	v_mul_f32_e64 v58, v112, v70
	v_mul_f32_e64 v59, v113, v71
	v_pk_mul_f32 v[56:57], v[110:111], v[68:69]
	s_nop 3
	v_add_co_u32_e32 v60, vcc, s12, v186
	v_mfma_f32_16x16x32_bf16 v[56:59], v[52:55], v[158:161], v[56:59]
	s_nop 0
	v_addc_co_u32_e32 v61, vcc, 0, v187, vcc
	s_mov_b32 s12, 0x1bf08000
	v_mfma_f32_16x16x32_bf16 v[110:113], v[52:55], v[0:3], v[56:59]
	v_mul_f32_e64 v54, v108, v82
	v_mul_f32_e64 v55, v109, v83
	v_pk_mul_f32 v[52:53], v[106:107], v[80:81]
	v_add_co_u32_e32 v62, vcc, s12, v186
	s_nop 0
	v_mfma_f32_16x16x32_bf16 v[52:55], v[64:67], v[158:161], v[52:55]
	v_addc_co_u32_e32 v63, vcc, 0, v187, vcc
	global_store_dword v[62:63], v154, off offset:-4096
	v_mfma_f32_16x16x32_bf16 v[106:109], v[64:67], v[0:3], v[52:55]
	global_store_dword v[60:61], v155, off offset:2048
	global_store_dword v[62:63], v156, off
	global_store_dword v[62:63], v157, off offset:2048
	s_barrier
	ds_read_b128 v[88:91], v204 offset:11008
	ds_read_b128 v[150:153], v204 offset:13056
	ds_read_b128 v[142:145], v205 offset:11008
	ds_read_b128 v[92:95], v205 offset:13056
	ds_read_b64 v[76:77], v206 offset:15104
	ds_read_b128 v[138:141], v207 offset:15616
	ds_read_b128 v[130:133], v207 offset:15872
	ds_read_b128 v[122:125], v207 offset:16128
	ds_read_b128 v[134:137], v208 offset:21824
	ds_read_b128 v[126:129], v208 offset:21888
	ds_read_b128 v[100:103], v208 offset:21760
	ds_read_b128 v[118:121], v207 offset:16384
	ds_read_b64 v[84:85], v209 offset:19712
	ds_read_b128 v[114:117], v208 offset:21952
	s_waitcnt vmcnt(9)
	ds_write_b128 v181, v[20:23]
	s_waitcnt vmcnt(8)
	ds_write_b128 v188, v[24:27]
	s_and_saveexec_b64 s[12:13], s[42:43]
	ds_write_b128 v189, v[28:31]
	s_or_b64 exec, exec, s[12:13]
	s_cmpk_gt_u32 s34, 0xf9
	s_cbranch_scc1 .LBB0_929
	v_add_co_u32_e32 v0, vcc, 0x4c57000, v176
	s_nop 1
	v_addc_co_u32_e32 v1, vcc, 0, v177, vcc
	v_add_co_u32_e32 v24, vcc, 0x4c58000, v176
	s_nop 1
	v_addc_co_u32_e32 v25, vcc, 0, v177, vcc
	global_load_dwordx4 v[20:23], v[0:1], off offset:512
	s_nop 0
	global_load_dwordx4 v[24:27], v[24:25], off offset:512
	s_and_saveexec_b64 s[12:13], s[42:43]
	s_cbranch_execz .LBB0_928
	v_add_co_u32_e32 v0, vcc, 0x4c59000, v176
	s_nop 1
	v_addc_co_u32_e32 v1, vcc, 0, v177, vcc
	global_load_dwordx4 v[28:31], v[0:1], off offset:512

.LBB0_929:
	v_cvt_pk_bf16_f32 v52, v96, v97
	v_cvt_pk_bf16_f32 v53, v98, v99
	v_cvt_pk_bf16_f32 v54, v146, v147
	v_cvt_pk_bf16_f32 v55, v148, v149
	v_cvt_pk_bf16_f32 v60, v110, v111
	v_cvt_pk_bf16_f32 v61, v112, v113
	s_nop 0
	v_lshlrev_b32_e32 v0, 16, v52
	v_and_b32_e32 v1, 0xffff0000, v52
	v_sub_f32_e32 v0, v96, v0
	v_sub_f32_e32 v1, v97, v1
	v_cvt_pk_bf16_f32 v56, v0, v1
	v_lshlrev_b32_e32 v0, 16, v53
	v_and_b32_e32 v1, 0xffff0000, v53
	v_sub_f32_e32 v0, v98, v0
	v_sub_f32_e32 v1, v99, v1
	s_waitcnt lgkmcnt(0)
	v_mfma_f32_16x16x32_bf16 v[66:69], v[150:153], v[52:55], 0
	v_cvt_pk_bf16_f32 v57, v0, v1
	v_lshlrev_b32_e32 v0, 16, v54
	v_and_b32_e32 v1, 0xffff0000, v54
	v_sub_f32_e32 v0, v146, v0
	v_sub_f32_e32 v1, v147, v1
	v_cvt_pk_bf16_f32 v58, v0, v1
	v_lshlrev_b32_e32 v0, 16, v55
	v_and_b32_e32 v1, 0xffff0000, v55
	v_sub_f32_e32 v0, v148, v0
	v_sub_f32_e32 v1, v149, v1
	v_cvt_pk_bf16_f32 v59, v0, v1
	v_lshlrev_b32_e32 v0, 16, v60
	v_mfma_f32_16x16x32_bf16 v[68:71], v[150:153], v[56:59], v[66:69]
	v_and_b32_e32 v1, 0xffff0000, v60
	v_sub_f32_e32 v0, v110, v0
	v_sub_f32_e32 v1, v111, v1
	v_cvt_pk_bf16_f32 v64, v0, v1
	v_lshlrev_b32_e32 v0, 16, v61
	v_and_b32_e32 v1, 0xffff0000, v61
	v_cvt_pk_bf16_f32 v62, v106, v107
	v_cvt_pk_bf16_f32 v63, v108, v109
	v_sub_f32_e32 v0, v112, v0
	v_sub_f32_e32 v1, v113, v1
	s_waitcnt lgkmcnt(12)
	v_mfma_f32_16x16x32_bf16 v[68:71], v[92:95], v[60:63], v[68:71]
	v_cvt_pk_bf16_f32 v65, v0, v1
	v_lshlrev_b32_e32 v0, 16, v62
	v_and_b32_e32 v1, 0xffff0000, v62
	v_mfma_f32_16x16x32_bf16 v[52:55], v[88:91], v[52:55], 0
	v_sub_f32_e32 v0, v106, v0
	v_sub_f32_e32 v1, v107, v1
	v_cvt_pk_bf16_f32 v66, v0, v1
	v_lshlrev_b32_e32 v0, 16, v63
	v_and_b32_e32 v1, 0xffff0000, v63
	v_mov_b32_e32 v78, v3
	v_mov_b32_e32 v79, v3
	v_sub_f32_e32 v0, v108, v0
	v_sub_f32_e32 v1, v109, v1
	v_cvt_pk_bf16_f32 v67, v0, v1
	v_mfma_f32_16x16x32_bf16 v[52:55], v[88:91], v[56:59], v[52:55]
	v_mov_b32_e32 v86, v3
	v_mov_b32_e32 v87, v3
	s_mov_b32 s12, 0x1bf0f000
	v_mfma_f32_16x16x32_bf16 v[68:71], v[92:95], v[64:67], v[68:71]
	s_waitcnt lgkmcnt(6)
	v_pk_mul_f32 v[112:113], v[128:129], v[112:113]
	v_pk_mul_f32 v[110:111], v[126:127], v[110:111]
	s_waitcnt lgkmcnt(2)
	v_pk_mul_f32 v[108:109], v[116:117], v[108:109]
	v_mfma_f32_16x16x32_bf16 v[156:159], v[76:79], v[84:87], v[68:71]
	v_mul_f32_e64 v106, v114, v106
	v_mul_f32_e64 v107, v115, v107
	s_waitcnt lgkmcnt(0)
	s_nop 0
	v_mfma_f32_16x16x32_bf16 v[68:71], v[142:145], v[60:63], v[52:55]
	s_nop 0
	s_nop 0
	s_nop 0
	s_nop 0
	s_nop 0
	s_nop 0
	s_nop 0
	s_nop 0
	v_mfma_f32_16x16x32_bf16 v[64:67], v[142:145], v[64:67], v[68:71]
	v_mov_b32_e32 v144, v84
	v_mov_b32_e32 v145, v85
	s_nop 0
	v_pk_mul_f32 v[70:71], v[102:103], v[98:99]
	v_pk_mul_f32 v[68:69], v[100:101], v[96:97]
	s_nop 2
	v_xor_b32_e32 v0, 0x80000000, v64
	v_xor_b32_e32 v1, 0x80000000, v65
	v_cvt_pk_bf16_f32 v142, v0, v1
	v_xor_b32_e32 v0, 0x80000000, v66
	v_xor_b32_e32 v1, 0x80000000, v67
	v_cvt_pk_bf16_f32 v143, v0, v1
	v_lshlrev_b32_e32 v0, 16, v142
	v_and_b32_e32 v1, 0xffff0000, v142
	v_sub_f32_e64 v0, -v64, v0
	v_sub_f32_e64 v1, -v65, v1
	v_mfma_f32_16x16x32_bf16 v[68:71], v[138:141], v[142:145], v[68:71]
	v_cvt_pk_bf16_f32 v0, v0, v1
	v_lshlrev_b32_e32 v1, 16, v143
	v_and_b32_e32 v2, 0xffff0000, v143
	v_sub_f32_e64 v1, -v66, v1
	v_sub_f32_e64 v2, -v67, v2
	v_pk_mul_f32 v[66:67], v[136:137], v[148:149]
	v_pk_mul_f32 v[64:65], v[134:135], v[146:147]
	v_cvt_pk_bf16_f32 v1, v1, v2
	v_mov_b32_e32 v2, v3
	v_add_co_u32_e32 v102, vcc, s12, v186
	v_mfma_f32_16x16x32_bf16 v[134:137], v[130:133], v[142:145], v[64:67]
	s_nop 0
	v_addc_co_u32_e32 v103, vcc, 0, v187, vcc
	s_mov_b32 s12, 0x1bf10000
	v_mfma_f32_16x16x32_bf16 v[110:113], v[122:125], v[142:145], v[110:113]
	v_add_co_u32_e32 v126, vcc, s12, v186
	v_mfma_f32_16x16x32_bf16 v[106:109], v[118:121], v[142:145], v[106:109]
	s_nop 0
	v_addc_co_u32_e32 v127, vcc, 0, v187, vcc
	v_mfma_f32_16x16x32_bf16 v[138:141], v[138:141], v[0:3], v[68:71]
	s_nop 0
	s_nop 1
	s_nop 0
	s_nop 0
	s_nop 0
	s_nop 0
	s_nop 0
	global_store_dword v[126:127], v156, off offset:-4096
	v_mfma_f32_16x16x32_bf16 v[146:149], v[130:133], v[0:3], v[134:137]
	global_store_dword v[102:103], v157, off offset:2048
	global_store_dword v[126:127], v158, off
	global_store_dword v[126:127], v159, off offset:2048
	s_barrier
	ds_read_b128 v[76:79], v204
	ds_read_b128 v[92:95], v204 offset:2048
	ds_read_b128 v[72:75], v205
	ds_read_b128 v[88:91], v205 offset:2048
	ds_read_b64 v[104:105], v206 offset:4096
	ds_read_b128 v[60:63], v207 offset:4608
	ds_read_b128 v[56:59], v207 offset:4864
	ds_read_b128 v[52:55], v207 offset:5120
	ds_read_b128 v[84:87], v208 offset:10816
	ds_read_b128 v[68:71], v208 offset:10880
	ds_read_b128 v[96:99], v208 offset:10752
	ds_read_b128 v[64:67], v207 offset:5376
	ds_read_b64 v[100:101], v209 offset:8704
	ds_read_b128 v[80:83], v208 offset:10944
	s_waitcnt vmcnt(11)
	ds_write_b128 v181, v[32:35] offset:11008
	s_waitcnt vmcnt(10)
	ds_write_b128 v188, v[36:39] offset:11008
	v_mfma_f32_16x16x32_bf16 v[152:155], v[122:125], v[0:3], v[110:113]
	v_mfma_f32_16x16x32_bf16 v[158:161], v[118:121], v[0:3], v[106:109]
	s_and_saveexec_b64 s[12:13], s[42:43]
	ds_write_b128 v189, v[40:43] offset:11008
	s_or_b64 exec, exec, s[12:13]
	s_cmpk_gt_u32 s34, 0xf8
	s_cbranch_scc1 .LBB0_935
	v_add_co_u32_e32 v0, vcc, 0x4c59000, v176
	s_nop 1
	v_addc_co_u32_e32 v1, vcc, 0, v177, vcc
	v_add_co_u32_e32 v36, vcc, 0x4c5a000, v176
	s_nop 1
	v_addc_co_u32_e32 v37, vcc, 0, v177, vcc
	global_load_dwordx4 v[32:35], v[0:1], off offset:3328
	s_nop 0
	global_load_dwordx4 v[36:39], v[36:37], off offset:3328
	s_and_saveexec_b64 s[12:13], s[42:43]
	s_cbranch_execz .LBB0_934
	v_add_co_u32_e32 v0, vcc, 0x4c5b000, v176
	s_nop 1
	v_addc_co_u32_e32 v1, vcc, 0, v177, vcc
	global_load_dwordx4 v[40:43], v[0:1], off offset:3328

.LBB0_935:
	v_cvt_pk_bf16_f32 v108, v138, v139
	v_cvt_pk_bf16_f32 v109, v140, v141
	v_cvt_pk_bf16_f32 v110, v146, v147
	v_cvt_pk_bf16_f32 v111, v148, v149
	v_cvt_pk_bf16_f32 v122, v152, v153
	v_cvt_pk_bf16_f32 v123, v154, v155
	s_nop 0
	v_lshlrev_b32_e32 v0, 16, v108
	v_and_b32_e32 v1, 0xffff0000, v108
	v_sub_f32_e32 v0, v138, v0
	v_sub_f32_e32 v1, v139, v1
	v_cvt_pk_bf16_f32 v112, v0, v1
	v_lshlrev_b32_e32 v0, 16, v109
	v_and_b32_e32 v1, 0xffff0000, v109
	v_sub_f32_e32 v0, v140, v0
	v_sub_f32_e32 v1, v141, v1
	s_waitcnt lgkmcnt(0)
	v_mfma_f32_16x16x32_bf16 v[116:119], v[92:95], v[108:111], 0
	v_cvt_pk_bf16_f32 v113, v0, v1
	v_lshlrev_b32_e32 v0, 16, v110
	v_and_b32_e32 v1, 0xffff0000, v110
	v_sub_f32_e32 v0, v146, v0
	v_sub_f32_e32 v1, v147, v1
	v_cvt_pk_bf16_f32 v114, v0, v1
	v_lshlrev_b32_e32 v0, 16, v111
	v_and_b32_e32 v1, 0xffff0000, v111
	v_sub_f32_e32 v0, v148, v0
	v_sub_f32_e32 v1, v149, v1
	v_cvt_pk_bf16_f32 v115, v0, v1
	v_lshlrev_b32_e32 v0, 16, v122
	v_mfma_f32_16x16x32_bf16 v[116:119], v[92:95], v[112:115], v[116:119]
	v_and_b32_e32 v1, 0xffff0000, v122
	v_sub_f32_e32 v0, v152, v0
	v_sub_f32_e32 v1, v153, v1
	v_cvt_pk_bf16_f32 v126, v0, v1
	v_lshlrev_b32_e32 v0, 16, v123
	v_and_b32_e32 v1, 0xffff0000, v123
	v_cvt_pk_bf16_f32 v124, v158, v159
	v_cvt_pk_bf16_f32 v125, v160, v161
	v_sub_f32_e32 v0, v154, v0
	v_sub_f32_e32 v1, v155, v1
	s_waitcnt lgkmcnt(12)
	v_mfma_f32_16x16x32_bf16 v[116:119], v[88:91], v[122:125], v[116:119]
	v_cvt_pk_bf16_f32 v127, v0, v1
	v_lshlrev_b32_e32 v0, 16, v124
	v_and_b32_e32 v1, 0xffff0000, v124
	v_sub_f32_e32 v0, v158, v0
	v_sub_f32_e32 v1, v159, v1
	v_cvt_pk_bf16_f32 v128, v0, v1
	v_lshlrev_b32_e32 v0, 16, v125
	v_and_b32_e32 v1, 0xffff0000, v125
	v_mov_b32_e32 v106, v3
	v_mov_b32_e32 v107, v3
	v_sub_f32_e32 v0, v160, v0
	v_sub_f32_e32 v1, v161, v1
	v_cvt_pk_bf16_f32 v129, v0, v1
	v_mov_b32_e32 v102, v3
	v_mfma_f32_16x16x32_bf16 v[116:119], v[88:91], v[126:129], v[116:119]
	v_mov_b32_e32 v103, v3
	s_waitcnt lgkmcnt(3)
	v_mov_b32_e32 v216, v100
	v_mov_b32_e32 v217, v101
	v_mfma_f32_16x16x32_bf16 v[210:213], v[104:107], v[100:103], v[116:119]
	v_mul_f32_e64 v154, v70, v154
	v_mul_f32_e64 v155, v71, v155
	v_pk_mul_f32 v[152:153], v[68:69], v[152:153]
	s_waitcnt lgkmcnt(2)
	v_pk_mul_f32 v[160:161], v[82:83], v[160:161]
	v_mfma_f32_16x16x32_bf16 v[106:109], v[76:79], v[108:111], 0
	v_mul_f32_e64 v158, v80, v158
	v_mul_f32_e64 v159, v81, v159
	s_waitcnt lgkmcnt(0)
	s_barrier
	v_mfma_f32_16x16x32_bf16 v[106:109], v[76:79], v[112:115], v[106:109]
	ds_read_b128 v[118:121], v204 offset:11008
	ds_read_b128 v[170:173], v204 offset:13056
	ds_read_b128 v[134:137], v205 offset:11008
	ds_read_b128 v[162:165], v205 offset:13056
	s_mov_b32 s12, 0x1bf17000
	v_mfma_f32_16x16x32_bf16 v[122:125], v[72:75], v[122:125], v[106:109]
	ds_read_b64 v[150:151], v206 offset:15104
	ds_read_b128 v[114:117], v207 offset:15616
	ds_read_b128 v[110:113], v207 offset:15872
	ds_read_b128 v[106:109], v207 offset:16128
	v_add_co_u32_e32 v102, vcc, s12, v186
	v_mfma_f32_16x16x32_bf16 v[122:125], v[72:75], v[126:129], v[122:125]
	v_mul_f32_e64 v128, v98, v140
	v_mul_f32_e64 v129, v99, v141
	v_pk_mul_f32 v[126:127], v[96:97], v[138:139]
	ds_read_b128 v[138:141], v208 offset:21824
	ds_read_b128 v[130:133], v208 offset:21888
	v_addc_co_u32_e32 v103, vcc, 0, v187, vcc
	s_nop 1
	v_xor_b32_e32 v0, 0x80000000, v122
	v_xor_b32_e32 v1, 0x80000000, v123
	v_cvt_pk_bf16_f32 v214, v0, v1
	v_xor_b32_e32 v0, 0x80000000, v124
	v_xor_b32_e32 v1, 0x80000000, v125
	v_cvt_pk_bf16_f32 v215, v0, v1
	v_lshlrev_b32_e32 v0, 16, v214
	v_and_b32_e32 v1, 0xffff0000, v214
	v_sub_f32_e64 v0, -v122, v0
	v_sub_f32_e64 v1, -v123, v1
	v_mfma_f32_16x16x32_bf16 v[126:129], v[60:63], v[214:217], v[126:129]
	v_cvt_pk_bf16_f32 v0, v0, v1
	v_lshlrev_b32_e32 v1, 16, v215
	v_and_b32_e32 v2, 0xffff0000, v215
	v_sub_f32_e64 v1, -v124, v1
	v_sub_f32_e64 v2, -v125, v2
	v_pk_mul_f32 v[124:125], v[86:87], v[148:149]
	v_pk_mul_f32 v[122:123], v[84:85], v[146:147]
	v_cvt_pk_bf16_f32 v1, v1, v2
	v_mov_b32_e32 v2, v3
	v_mfma_f32_16x16x32_bf16 v[152:155], v[52:55], v[214:217], v[152:155]
	s_mov_b32 s12, 0x1bf18000
	s_cmpk_lt_u32 s34, 0xfc
	v_add_co_u32_e32 v218, vcc, s12, v186
	v_mfma_f32_16x16x32_bf16 v[146:149], v[56:59], v[214:217], v[122:125]
	s_cselect_b64 s[12:13], -1, 0
	s_cmpk_gt_u32 s34, 0xfb
	v_addc_co_u32_e32 v219, vcc, 0, v187, vcc
	v_mfma_f32_16x16x32_bf16 v[158:161], v[64:67], v[214:217], v[158:161]
	s_cselect_b64 s[40:41], -1, 0
	s_and_b64 vcc, exec, s[40:41]
	v_mfma_f32_16x16x32_bf16 v[142:145], v[60:63], v[0:3], v[126:129]
	ds_read_b128 v[166:169], v208 offset:21760
	ds_read_b128 v[122:125], v207 offset:16384
	ds_read_b64 v[174:175], v209 offset:19712
	ds_read_b128 v[126:129], v208 offset:21952
	global_store_dword v[218:219], v210, off offset:-4096
	global_store_dword v[102:103], v211, off offset:2048
	global_store_dword v[218:219], v212, off
	global_store_dword v[218:219], v213, off offset:2048
	v_mfma_f32_16x16x32_bf16 v[146:149], v[56:59], v[0:3], v[146:149]
	v_mfma_f32_16x16x32_bf16 v[154:157], v[52:55], v[0:3], v[152:155]
	v_mfma_f32_16x16x32_bf16 v[158:161], v[64:67], v[0:3], v[158:161]
	s_cbranch_vccnz .LBB0_939
	s_waitcnt vmcnt(13)
	ds_write_b128 v181, v[44:47]
	s_waitcnt vmcnt(12)
	ds_write_b128 v188, v[48:51]
	s_and_saveexec_b64 s[50:51], s[42:43]
	ds_write_b128 v189, v[4:7]
	s_or_b64 exec, exec, s[50:51]
